# team-1 W_in column-block transposes store WINT with nt (streaming), like the W_out transposes; on top of batched stats_rows
# baseline (speedup 1.0000x reference)
.LBB0_102:
	s_mul_hi_i32 s16, s16, 0x2aaaaaab
	s_lshr_b32 s17, s16, 31
	s_ashr_i32 s16, s16, 4
	s_add_i32 s16, s16, s17
	s_mul_i32 s17, s16, 0xfffffa00
	s_add_i32 s17, s11, s17
	s_and_b32 s17, s17, 0x7fffffc0
	s_add_i32 s16, s17, s16
	s_ashr_i32 s17, s16, 31
	s_and_b32 s18, s10, 0x3000
	s_lshl_b64 s[16:17], s[16:17], 15
	s_add_u32 s16, s70, s16
	s_waitcnt lgkmcnt(0)
	v_add_u32_e32 v67, 0x400, v112
	s_addc_u32 s17, s71, s17
	s_lshl_b32 s18, s18, 1
	ds_read2_b32 v[118:119], v112 offset0:65 offset1:73
	ds_read2_b32 v[120:121], v112 offset1:8
	ds_read2_b32 v[122:123], v112 offset0:130 offset1:138
	ds_read2_b32 v[124:125], v112 offset0:195 offset1:203
	ds_read2_b32 v[126:127], v67 offset0:4 offset1:12
	ds_read2_b32 v[128:129], v67 offset0:69 offset1:77
	ds_read2_b32 v[130:131], v67 offset0:134 offset1:142
	ds_read2_b32 v[132:133], v67 offset0:199 offset1:207
	s_add_u32 s16, s16, s18
	s_addc_u32 s17, s17, 0
	v_lshl_add_u64 v[134:135], s[16:17], 0, v[64:65]
	v_mov_b32_e32 v97, v65
	v_lshl_add_u64 v[136:137], v[134:135], 0, v[96:97]
	s_waitcnt lgkmcnt(6)
	v_cvt_pk_bf16_f32 v114, v120, v118
	s_waitcnt lgkmcnt(4)
	v_cvt_pk_bf16_f32 v115, v122, v124
	s_waitcnt lgkmcnt(2)
	v_cvt_pk_bf16_f32 v116, v126, v128
	s_waitcnt lgkmcnt(0)
	v_cvt_pk_bf16_f32 v117, v130, v132
	global_store_dwordx4 v[136:137], v[114:117], off nt
	v_mov_b32_e32 v99, v65
	v_mov_b32_e32 v101, v65
	v_cvt_pk_bf16_f32 v114, v121, v119
	v_cvt_pk_bf16_f32 v115, v123, v125
	v_cvt_pk_bf16_f32 v116, v127, v129
	v_cvt_pk_bf16_f32 v117, v131, v133
	ds_read2_b32 v[120:121], v112 offset0:16 offset1:24
	ds_read2_b32 v[122:123], v112 offset0:81 offset1:89
	ds_read2_b32 v[124:125], v112 offset0:146 offset1:154
	ds_read2_b32 v[126:127], v112 offset0:211 offset1:219
	ds_read2_b32 v[128:129], v67 offset0:20 offset1:28
	ds_read2_b32 v[130:131], v67 offset0:85 offset1:93
	ds_read2_b32 v[132:133], v67 offset0:150 offset1:158
	ds_read2_b32 v[136:137], v67 offset0:215 offset1:223
	v_lshl_add_u64 v[118:119], v[134:135], 0, v[98:99]
	global_store_dwordx4 v[118:119], v[114:117], off nt
	v_lshl_add_u64 v[118:119], v[134:135], 0, v[100:101]
	v_mov_b32_e32 v103, v65
	s_waitcnt lgkmcnt(6)
	v_cvt_pk_bf16_f32 v114, v120, v122
	s_waitcnt lgkmcnt(4)
	v_cvt_pk_bf16_f32 v115, v124, v126
	s_waitcnt lgkmcnt(2)
	v_cvt_pk_bf16_f32 v116, v128, v130
	s_waitcnt lgkmcnt(0)
	v_cvt_pk_bf16_f32 v117, v132, v136
	global_store_dwordx4 v[118:119], v[114:117], off nt
	v_lshl_add_u64 v[118:119], v[134:135], 0, v[102:103]
	v_mov_b32_e32 v105, v65
	v_cvt_pk_bf16_f32 v114, v121, v123
	v_cvt_pk_bf16_f32 v115, v125, v127
	v_cvt_pk_bf16_f32 v116, v129, v131
	v_cvt_pk_bf16_f32 v117, v133, v137
	ds_read2_b32 v[120:121], v112 offset0:32 offset1:40
	ds_read2_b32 v[122:123], v112 offset0:97 offset1:105
	ds_read2_b32 v[124:125], v112 offset0:162 offset1:170
	ds_read2_b32 v[126:127], v112 offset0:227 offset1:235
	ds_read2_b32 v[128:129], v67 offset0:36 offset1:44
	ds_read2_b32 v[130:131], v67 offset0:101 offset1:109
	ds_read2_b32 v[132:133], v67 offset0:166 offset1:174
	ds_read2_b32 v[136:137], v67 offset0:231 offset1:239
	global_store_dwordx4 v[118:119], v[114:117], off nt
	v_lshl_add_u64 v[118:119], v[134:135], 0, v[104:105]
	v_mov_b32_e32 v107, v65
	s_waitcnt lgkmcnt(6)
	v_cvt_pk_bf16_f32 v114, v120, v122
	s_waitcnt lgkmcnt(4)
	v_cvt_pk_bf16_f32 v115, v124, v126
	s_waitcnt lgkmcnt(2)
	v_cvt_pk_bf16_f32 v116, v128, v130
	s_waitcnt lgkmcnt(0)
	v_cvt_pk_bf16_f32 v117, v132, v136
	global_store_dwordx4 v[118:119], v[114:117], off nt
	v_lshl_add_u64 v[118:119], v[134:135], 0, v[106:107]
	v_mov_b32_e32 v109, v65
	v_cvt_pk_bf16_f32 v114, v121, v123
	v_cvt_pk_bf16_f32 v115, v125, v127
	v_cvt_pk_bf16_f32 v116, v129, v131
	v_cvt_pk_bf16_f32 v117, v133, v137
	ds_read2_b32 v[120:121], v112 offset0:48 offset1:56
	ds_read2_b32 v[122:123], v112 offset0:113 offset1:121
	ds_read2_b32 v[124:125], v112 offset0:178 offset1:186
	ds_read2_b32 v[126:127], v112 offset0:243 offset1:251
	ds_read2_b32 v[128:129], v67 offset0:52 offset1:60
	ds_read2_b32 v[130:131], v67 offset0:117 offset1:125
	ds_read2_b32 v[132:133], v67 offset0:182 offset1:190
	ds_read2_b32 v[136:137], v67 offset0:247 offset1:255
	global_store_dwordx4 v[118:119], v[114:117], off nt
	v_lshl_add_u64 v[118:119], v[134:135], 0, v[108:109]
	v_mov_b32_e32 v111, v65
	s_waitcnt lgkmcnt(6)
	v_cvt_pk_bf16_f32 v114, v120, v122
	s_waitcnt lgkmcnt(4)
	v_cvt_pk_bf16_f32 v115, v124, v126
	s_waitcnt lgkmcnt(2)
	v_cvt_pk_bf16_f32 v116, v128, v130
	s_waitcnt lgkmcnt(0)
	v_cvt_pk_bf16_f32 v117, v132, v136
	global_store_dwordx4 v[118:119], v[114:117], off nt
	v_lshl_add_u64 v[118:119], v[134:135], 0, v[110:111]
	s_add_i32 s10, s10, 0x400000
	v_cvt_pk_bf16_f32 v114, v121, v123
	v_cvt_pk_bf16_f32 v115, v125, v127
	v_cvt_pk_bf16_f32 v116, v129, v131
	v_cvt_pk_bf16_f32 v117, v133, v137
	global_store_dwordx4 v[118:119], v[114:117], off nt
	s_waitcnt lgkmcnt(0)
	s_addk_i32 s11, 0x4000
	s_add_i32 s14, s14, 0x10000
	s_andn2_b64 vcc, exec, s[6:7]
	s_mov_b32 s16, s15
	s_cbranch_vccz .LBB0_105
